# attention: running-max shift as 16-VGPR MFMA C operand (no extra MFMAs) + deferred check + baseline byte alignment downstream
# speedup vs baseline: 1.0070x; 1.0009x over previous
; #define LAS __attribute__((address_space(3)))
; template <int MODE> __device__ __forceinline__ void attn_unit(const bf16_t* __restrict__ Q, const bf16_t* __restrict__ KV, const bf16_t* __restrict__ KR, bf16_t* __restrict__ O,
;                                           long rowbase, int q0, int h, LAS char* lds) {
;   const int tid = threadIdx.x, lane = tid & 63, r32 = lane & 31, hi = lane >> 5; const int wid = __builtin_amdgcn_readfirstlane(tid >> 6);
;   LAS char* Kl = lds + LDS_K; LAS char* Vl = lds + LDS_V;
;   LAS float* ws = (LAS float*)(lds + LDS_WS) + wid * 64; LAS float* li_l = ws; LAS float* al_l = ws + 32;
;   const bf16_t* Kw = KV + (rowbase + lane) * LDKV + h * 128 + wid * 8;
;   const bf16_t* KRw = KR + (rowbase + lane) * LDKR + (wid & 3) * 8;
;   const bf16_t* Vw = KV + (rowbase + 16 * (wid & 3) + (lane >> 2)) * LDKV + h * 128 + 64 + (wid >> 2) * 32 + (lane & 3) * 8;
;     ...
;   float m_reg = -1e30f, l_reg = 0; f32x16 o[2] = {}; bf16x8 qr[6];
;   const bf16_t* Qw = Q + (rowbase + q0 + wid * QBLK + r32) * LDQ + h * QKD + hi * 8;
; #pragma unroll
;   for (int d0 = 0; d0 < 6; ++d0) qr[d0] = *reinterpret_cast<const bf16x8*>(Qw + d0 * 16);
;   asm volatile("" ::: "memory");
;   ISSUE(0, 0, 0); ISSUE(1, KSLOT, VSLOT);
;   const int vbase = (int)(unsigned)(uintptr_t)Vl + ((lane >> 4) & 1) * 32 + (lane & 3) * 8 + (4 * hi + ((lane & 15) >> 2)) * 64;
;   f32x16 pA0, pA1, pB0, pB1; float mnA, mnB, alA, alB; bf16x8 pa0, pa1, pa2, pa3; constexpr int NT = SEQ / KVBLK;
;   int kprev = 2 * KSLOT, kcur = 0, knext = KSLOT;
;     ...
;   if (hi == 0) li_l[r32] = l_reg; asm volatile("s_waitcnt lgkmcnt(0)" ::: "memory");
;   float rli[16];
; #pragma unroll
;   for (int r = 0; r < 16; ++r) rli[r] = __builtin_amdgcn_rcpf(li_l[crow(r, hi)]);
;   bf16_t* Ow = O + (rowbase + q0 + wid * QBLK) * LDO + h * VD;
;   {
;     LAS bf16_t* stg = (LAS bf16_t*)(lds + LDS_OST) + wid * 2048;
; #pragma unroll
;     for (int r = 0; r < 16; ++r) { const int orow = crow(r, hi);
; #pragma unroll
;       for (int d0 = 0; d0 < 2; ++d0) stg[orow * 64 + d0 * 32 + r32] = (bf16_t)(cvt_pk_bf16(o[d0][r] * rli[r], 0.f) & 0xffffu); }
;     asm volatile("s_waitcnt lgkmcnt(0)" ::: "memory");
; #pragma unroll
;     for (int i = 0; i < 4; ++i) { const int row = i * 8 + (lane >> 3), ch = lane & 7; const u32x4 v = *(const LAS u32x4*)(stg + row * 64 + ch * 8); *(u32x4*)(Ow + (long)row * LDO + ch * 8) = v; }
;   }
.LBB0_550:
	s_cmp_lt_i32 s30, 4
	s_cselect_b64 s[2:3], -1, 0
	s_and_b64 s[0:1], s[2:3], s[0:1]
	s_cmpk_lt_i32 s22, 0xa00
	s_cselect_b64 s[2:3], -1, 0
	s_and_b64 s[2:3], s[0:1], s[2:3]
	s_andn2_b64 vcc, exec, s[2:3]
	s_cbranch_vccnz .LBB0_606
	v_lshlrev_b32_e32 v3, 3, v195
	v_lshlrev_b32_e32 v4, 1, v195
	v_lshrrev_b32_e32 v1, 5, v194
	v_and_b32_e32 v0, 24, v3
	v_and_b32_e32 v4, 32, v4
	v_lshlrev_b32_e32 v6, 4, v195
	s_add_i32 s2, 0, 0xc000
	v_lshlrev_b32_e32 v2, 3, v1
	v_lshlrev_b32_e32 v5, 8, v1
	v_and_b32_e32 v6, 0xc0, v6
	v_add3_u32 v4, v4, s2, v0
	v_lshlrev_b32_e32 v203, 10, v1
	v_lshlrev_b32_e32 v232, 4, v1
	v_lshlrev_b32_e32 v235, 9, v1
	v_lshrrev_b32_e32 v1, 3, v194
	v_add3_u32 v197, v4, v6, v5
	v_and_b32_e32 v4, 56, v3
	v_or_b32_e32 v3, 8, v1
	v_and_b32_e32 v192, 31, v195
	v_lshlrev_b32_e32 v236, 7, v1
	v_lshlrev_b32_e32 v6, 10, v1
	v_lshlrev_b32_e32 v8, 10, v3
	v_or_b32_e32 v3, 16, v1
	v_or_b32_e32 v1, 24, v1
	v_mov_b32_e32 v199, 0
	v_lshlrev_b32_e32 v230, 4, v192
	s_waitcnt lgkmcnt(0)
	v_lshlrev_b32_e32 v10, 10, v3
	v_lshlrev_b32_e32 v12, 10, v1
	v_and_b32_e32 v1, 3, v195
	v_lshrrev_b32_e32 v193, 2, v194
	s_mov_b32 s7, 0
	v_add3_u32 v231, 0, v203, v230
	v_cmp_gt_u32_e64 s[2:3], 32, v194
	v_add_u32_e32 v233, 0x4000, v197
	v_add_u32_e32 v234, 0x6000, v197
	v_lshlrev_b32_e32 v200, 6, v194
	v_mov_b32_e32 v201, v199
	v_lshlrev_b32_e32 v202, 4, v1
	v_lshlrev_b32_e32 v204, 11, v194
	v_mov_b32_e32 v205, v199
	v_lshlrev_b32_e32 v206, 1, v2
	v_mov_b32_e32 v207, v199
	v_lshlrev_b32_e32 v208, 1, v0
	v_mov_b32_e32 v209, v199
	s_mov_b64 s[8:9], 0x20000
	s_mov_b64 s[10:11], 0x40000
	s_mov_b64 s[12:13], 0x2000
	s_mov_b32 s23, 0x4138aa3b
	s_mov_b64 s[14:15], 0x29c08000
	s_mov_b64 s[16:17], 0x1fc84080
	s_mov_b64 s[18:19], 0x1fca4000
	s_mov_b64 s[24:25], 0x29c09000
	s_mov_b64 s[54:55], 0x1fca4080
	v_lshlrev_b32_e32 v198, 1, v4
	v_lshlrev_b32_e32 v210, 1, v6
	v_lshlrev_b32_e32 v212, 1, v8
	v_lshlrev_b32_e32 v214, 1, v10
	v_lshlrev_b32_e32 v216, 1, v12
	v_mov_b64_e32 v[218:219], s[52:53]
	s_branch .LBB0_553
.LBB0_552:
	s_or_b64 exec, exec, s[4:5]
	s_waitcnt lgkmcnt(0)
	v_add_u32_e32 v40, s62, v232
	ds_read_b128 v[32:35], v40
	ds_read_b128 v[36:39], v40 offset:32
	s_lshl_b32 s6, s35, 12
	s_add_i32 s6, s6, 0
	s_add_i32 s6, s6, 0x18800
	s_waitcnt lgkmcnt(0)
	v_rcp_f32_e32 v41, v32
	v_rcp_f32_e32 v42, v33
	v_rcp_f32_e32 v43, v34
	v_rcp_f32_e32 v44, v35
	v_rcp_f32_e32 v45, v36
	ds_read_b128 v[32:35], v40 offset:64
	v_rcp_f32_e32 v46, v37
	v_rcp_f32_e32 v47, v38
	v_rcp_f32_e32 v48, v39
	ds_read_b128 v[36:39], v40 offset:96
	v_lshlrev_b32_e32 v40, 1, v192
	v_mul_f32_e32 v0, v0, v41
	v_add3_u32 v40, s6, v235, v40
	v_cvt_pk_bf16_f32 v0, v0, v199
	ds_write_b16 v40, v0
	v_mul_f32_e32 v0, v16, v41
	v_cvt_pk_bf16_f32 v0, v0, v199
	ds_write_b16 v40, v0 offset:64
	v_mul_f32_e32 v0, v1, v42
	v_cvt_pk_bf16_f32 v0, v0, v199
	ds_write_b16 v40, v0 offset:128
	v_mul_f32_e32 v0, v17, v42
	v_cvt_pk_bf16_f32 v0, v0, v199
	ds_write_b16 v40, v0 offset:192
	v_mul_f32_e32 v0, v2, v43
	v_cvt_pk_bf16_f32 v0, v0, v199
	ds_write_b16 v40, v0 offset:256
	v_mul_f32_e32 v0, v18, v43
	v_cvt_pk_bf16_f32 v0, v0, v199
	ds_write_b16 v40, v0 offset:320
	v_mul_f32_e32 v0, v3, v44
	v_cvt_pk_bf16_f32 v0, v0, v199
	ds_write_b16 v40, v0 offset:384
	v_mul_f32_e32 v0, v19, v44
	v_cvt_pk_bf16_f32 v0, v0, v199
	ds_write_b16 v40, v0 offset:448
	v_mul_f32_e32 v0, v4, v45
	v_cvt_pk_bf16_f32 v0, v0, v199
	ds_write_b16 v40, v0 offset:1024
	v_mul_f32_e32 v0, v20, v45
	v_cvt_pk_bf16_f32 v0, v0, v199
	ds_write_b16 v40, v0 offset:1088
	v_mul_f32_e32 v0, v5, v46
	v_cvt_pk_bf16_f32 v0, v0, v199
	ds_write_b16 v40, v0 offset:1152
	v_mul_f32_e32 v0, v21, v46
	v_cvt_pk_bf16_f32 v0, v0, v199
	ds_write_b16 v40, v0 offset:1216
	v_mul_f32_e32 v0, v6, v47
	v_cvt_pk_bf16_f32 v0, v0, v199
	ds_write_b16 v40, v0 offset:1280
	v_mul_f32_e32 v0, v22, v47
	v_cvt_pk_bf16_f32 v0, v0, v199
	s_waitcnt lgkmcnt(0)
	v_rcp_f32_e32 v32, v32
	ds_write_b16 v40, v0 offset:1344
	v_mul_f32_e32 v0, v7, v48
	v_cvt_pk_bf16_f32 v0, v0, v199
	ds_write_b16 v40, v0 offset:1408
	v_mul_f32_e32 v0, v23, v48
	v_cvt_pk_bf16_f32 v0, v0, v199
	v_rcp_f32_e32 v33, v33
	ds_write_b16 v40, v0 offset:1472
	v_mul_f32_e32 v0, v8, v32
	v_cvt_pk_bf16_f32 v0, v0, v199
	ds_write_b16 v40, v0 offset:2048
	v_mul_f32_e32 v0, v24, v32
	v_cvt_pk_bf16_f32 v0, v0, v199
	v_rcp_f32_e32 v34, v34
	ds_write_b16 v40, v0 offset:2112
	v_mul_f32_e32 v0, v9, v33
	v_cvt_pk_bf16_f32 v0, v0, v199
	ds_write_b16 v40, v0 offset:2176
	v_mul_f32_e32 v0, v25, v33
	v_cvt_pk_bf16_f32 v0, v0, v199
	v_rcp_f32_e32 v35, v35
	ds_write_b16 v40, v0 offset:2240
	v_mul_f32_e32 v0, v10, v34
	v_cvt_pk_bf16_f32 v0, v0, v199
	ds_write_b16 v40, v0 offset:2304
	v_mul_f32_e32 v0, v26, v34
	v_cvt_pk_bf16_f32 v0, v0, v199
	v_rcp_f32_e32 v36, v36
	ds_write_b16 v40, v0 offset:2368
	v_mul_f32_e32 v0, v11, v35
	v_cvt_pk_bf16_f32 v0, v0, v199
	ds_write_b16 v40, v0 offset:2432
	v_mul_f32_e32 v0, v27, v35
	v_cvt_pk_bf16_f32 v0, v0, v199
	v_rcp_f32_e32 v37, v37
	ds_write_b16 v40, v0 offset:2496
	v_mul_f32_e32 v0, v12, v36
	v_cvt_pk_bf16_f32 v0, v0, v199
	ds_write_b16 v40, v0 offset:3072
	v_mul_f32_e32 v0, v28, v36
	v_cvt_pk_bf16_f32 v0, v0, v199
	v_rcp_f32_e32 v38, v38
	ds_write_b16 v40, v0 offset:3136
	v_mul_f32_e32 v0, v13, v37
	v_cvt_pk_bf16_f32 v0, v0, v199
	ds_write_b16 v40, v0 offset:3200
	v_mul_f32_e32 v0, v29, v37
	v_cvt_pk_bf16_f32 v0, v0, v199
	v_rcp_f32_e32 v39, v39
	ds_write_b16 v40, v0 offset:3264
	v_mul_f32_e32 v0, v14, v38
	v_cvt_pk_bf16_f32 v0, v0, v199
	ds_write_b16 v40, v0 offset:3328
	v_mul_f32_e32 v0, v30, v38
	v_cvt_pk_bf16_f32 v0, v0, v199
	ds_write_b16 v40, v0 offset:3392
	v_mul_f32_e32 v0, v15, v39
	v_cvt_pk_bf16_f32 v0, v0, v199
	ds_write_b16 v40, v0 offset:3456
	v_mul_f32_e32 v0, v31, v39
	s_lshl_b64 s[4:5], s[52:53], 11
	v_cvt_pk_bf16_f32 v0, v0, v199
	ds_write_b16 v40, v0 offset:3520
	v_add_u32_e32 v12, s6, v198
	s_add_u32 s4, s40, s4
	s_waitcnt lgkmcnt(0)
	v_add_u32_e32 v0, v12, v236
	s_addc_u32 s5, s41, s5
	s_lshl_b32 s34, s34, 7
	ds_read_b128 v[0:3], v0
	v_add_u32_e32 v4, v12, v236
	s_add_u32 s4, s4, s34
	ds_read_b128 v[4:7], v4 offset:1024
	s_addc_u32 s5, s5, 0
	v_lshl_add_u64 v[8:9], s[4:5], 0, v[198:199]
	v_mov_b32_e32 v211, v199
	v_lshl_add_u64 v[10:11], v[8:9], 0, v[210:211]
	v_mov_b32_e32 v213, v199
	s_waitcnt lgkmcnt(0)
	global_store_dwordx4 v[10:11], v[0:3], off
	v_mov_b32_e32 v215, v199
	v_lshl_add_u64 v[10:11], v[8:9], 0, v[214:215]
	v_lshl_add_u64 v[0:1], v[8:9], 0, v[212:213]
	global_store_dwordx4 v[0:1], v[4:7], off
	v_add_u32_e32 v0, v12, v236
	ds_read_b128 v[0:3], v0 offset:2048
	v_add_u32_e32 v4, v12, v236
	ds_read_b128 v[4:7], v4 offset:3072
	v_mov_b32_e32 v217, v199
	s_add_i32 s22, s22, s92
	s_waitcnt lgkmcnt(0)
	global_store_dwordx4 v[10:11], v[0:3], off
	s_cmpk_lt_i32 s22, 0xa00
	s_nop 0
	v_lshl_add_u64 v[0:1], v[8:9], 0, v[216:217]
	global_store_dwordx4 v[0:1], v[4:7], off
	s_waitcnt vmcnt(0) lgkmcnt(0)
	s_barrier
	s_cbranch_scc0 .LBB0_605
; #define LAS __attribute__((address_space(3)))
; #define ISSUE(t, ks, vs) do { GL(Kw + (long)(t) * KVBLK * LDKV, Kl + (ks) + wid * 1024); if (wid < 4) GL(KRw + (long)(t) * KVBLK * LDKR, Kl + (ks) + (8 + wid) * 1024); \
;     GL(Vw + (long)(t) * KVBLK * LDKV, Vl + (vs) + wid * 1024); } while (0)
; #define VMW_PART() do { if (wid < 4) asm volatile("s_waitcnt vmcnt(3) lgkmcnt(0)" ::: "memory"); else asm volatile("s_waitcnt vmcnt(2) lgkmcnt(0)" ::: "memory"); } while (0)
; #define BAR() do { SBAR(); __builtin_amdgcn_s_barrier(); asm volatile("" ::: "memory"); SBAR(); } while (0)
; template <int MODE> __device__ __forceinline__ void attn_unit(const bf16_t* __restrict__ Q, const bf16_t* __restrict__ KV, const bf16_t* __restrict__ KR, bf16_t* __restrict__ O,
;                                           long rowbase, int q0, int h, LAS char* lds) {
;   const int tid = threadIdx.x, lane = tid & 63, r32 = lane & 31, hi = lane >> 5; const int wid = __builtin_amdgcn_readfirstlane(tid >> 6);
;   LAS char* Kl = lds + LDS_K; LAS char* Vl = lds + LDS_V;
;   LAS float* ws = (LAS float*)(lds + LDS_WS) + wid * 64; LAS float* li_l = ws; LAS float* al_l = ws + 32;
;   const bf16_t* Kw = KV + (rowbase + lane) * LDKV + h * 128 + wid * 8;
;   const bf16_t* KRw = KR + (rowbase + lane) * LDKR + (wid & 3) * 8;
;   const bf16_t* Vw = KV + (rowbase + 16 * (wid & 3) + (lane >> 2)) * LDKV + h * 128 + 64 + (wid >> 2) * 32 + (lane & 3) * 8;
;     ...
;   float m_reg = -1e30f, l_reg = 0; f32x16 o[2] = {}; bf16x8 qr[6];
;   const bf16_t* Qw = Q + (rowbase + q0 + wid * QBLK + r32) * LDQ + h * QKD + hi * 8;
; #pragma unroll
;   for (int d0 = 0; d0 < 6; ++d0) qr[d0] = *reinterpret_cast<const bf16x8*>(Qw + d0 * 16);
;   asm volatile("" ::: "memory");
;   ISSUE(0, 0, 0); ISSUE(1, KSLOT, VSLOT);
;   const int vbase = (int)(unsigned)(uintptr_t)Vl + ((lane >> 4) & 1) * 32 + (lane & 3) * 8 + (4 * hi + ((lane & 15) >> 2)) * 64;
;   f32x16 pA0, pA1, pB0, pB1; float mnA, mnB, alA, alB; bf16x8 pa0, pa1, pa2, pa3; constexpr int NT = SEQ / KVBLK;
;   int kprev = 2 * KSLOT, kcur = 0, knext = KSLOT;
;     ...
;   bf16x8 kf[12]; s16x4 vf[16];
;   VMW_PART(); BAR();
;   if (wid >= 4) BAR();
;   ISSUE(2, 2 * KSLOT, 2 * VSLOT); kload12(kf, Kl, r32, hi); VMW_PART(); BAR();
.LBB0_553:
	s_ashr_i32 s58, s22, 7
	v_readfirstlane_b32 s68, v195
	s_ashr_i32 s59, s58, 31
	s_lshl_b32 s6, s22, 8
	s_lshr_b32 s35, s68, 6
	s_bfe_u32 s34, s22, 0x30004
	s_lshl_b64 s[4:5], s[58:59], 12
	s_and_b32 s52, s6, 0xf00
	s_lshl_b32 s56, s35, 4
	s_and_b32 s60, s56, 48
	s_lshl_b32 s6, s34, 8
	s_or_b32 s52, s4, s52
	s_lshl_b32 s53, s35, 5
	s_add_u32 s52, s52, s53
	v_or_b32_e32 v2, s52, v192
	s_movk_i32 s57, 0x600
	s_addc_u32 s53, s5, 0
	v_mad_u64_u32 v[2:3], s[62:63], v2, s57, v[218:219]
	v_mov_b32_e32 v8, 0x600
	v_mad_i32_i24 v3, s53, v8, v3
	s_mul_i32 s62, s34, 0xc0
	s_mov_b32 s63, s7
	v_lshl_add_u64 v[2:3], v[2:3], 0, s[62:63]
	v_lshl_add_u64 v[2:3], v[2:3], 0, v[206:207]
	v_mov_b32_e32 v5, s5
	v_or_b32_e32 v4, s4, v194
	global_load_dwordx4 v[116:119], v[2:3], off
	global_load_dwordx4 v[112:115], v[2:3], off offset:32
	global_load_dwordx4 v[108:111], v[2:3], off offset:64
	global_load_dwordx4 v[104:107], v[2:3], off offset:96
	global_load_dwordx4 v[100:103], v[2:3], off offset:128
	global_load_dwordx4 v[96:99], v[2:3], off offset:160
	v_lshlrev_b64 v[0:1], 11, v[4:5]
	v_lshl_add_u64 v[0:1], s[42:43], 0, v[0:1]
	s_lshl_b32 s64, s35, 10
	v_lshl_add_u64 v[0:1], v[0:1], 0, s[6:7]
	s_mov_b32 s57, s7
	s_add_i32 s65, s64, 0
	v_lshl_add_u64 v[0:1], v[0:1], 0, s[56:57]
	v_or_b32_e32 v2, s60, v193
	v_or_b32_e32 v2, s4, v2
	v_mov_b32_e32 v3, s5
	v_lshlrev_b64 v[2:3], 11, v[2:3]
	v_lshl_add_u64 v[2:3], s[42:43], 0, v[2:3]
	s_lshr_b32 s84, s68, 2
	v_lshl_add_u64 v[2:3], v[2:3], 0, s[6:7]
	s_and_b32 s6, s84, 0x3fffffc0
	s_cmpk_lt_u32 s68, 0x100
	v_lshl_add_u64 v[2:3], v[2:3], 0, s[6:7]
	s_cselect_b64 s[62:63], -1, 0
	s_cmpk_gt_u32 s68, 0xff
	v_lshl_add_u64 v[2:3], v[2:3], 0, v[208:209]
	s_cselect_b64 s[56:57], -1, 0
	s_mov_b64 s[4:5], 0x80
	v_lshl_add_u64 v[2:3], v[2:3], 0, s[4:5]
	v_lshlrev_b64 v[4:5], 6, v[4:5]
	v_lshl_add_u64 v[4:5], s[46:47], 0, v[4:5]
	s_mov_b32 s61, s7
	v_lshl_add_u64 v[4:5], v[4:5], 0, s[60:61]
	s_mov_b64 s[4:5], s[56:57]
	s_and_b64 vcc, exec, s[4:5]
	s_cbranch_vccnz .Lpr_nr0
	s_add_i32 m0, s65, 0x2000
	s_nop 0
	global_load_lds_dwordx4 v[4:5], off
	s_mov_b64 s[98:99], 0x1000
	v_lshl_add_u64 v[6:7], v[4:5], 0, s[98:99]
	s_add_i32 m0, s65, 0x5000
	s_nop 0
	global_load_lds_dwordx4 v[6:7], off
	v_lshl_add_u64 v[6:7], v[4:5], 0, s[12:13]
	s_add_i32 m0, s65, 0x8000
	s_nop 0
	global_load_lds_dwordx4 v[6:7], off

; #define FMA_S(x) asm("v_fma_f32 %0, %1, %2, %3" : "=v"(x) : "v"(x), "v"(Cv), "v"(mnC))
; __device__ __forceinline__ void partialSM(f32x16& p0, f32x16& p1, float& m_reg, float& mn, float& alpha) {
;   constexpr float C = SCALE * 1.4426950408889634f;
;   float pmax = p0[0];
; #pragma unroll
;   for (int r = 1; r < 16; ++r) pmax = fmaxf(pmax, p0[r]);
; #pragma unroll
;   for (int r = 0; r < 16; ++r) pmax = fmaxf(pmax, p1[r]);
;   { auto rr = __builtin_amdgcn_permlane32_swap(__float_as_uint(pmax), __float_as_uint(pmax), false, false);
;     pmax = fmaxf(__uint_as_float(rr[0]), __uint_as_float(rr[1])); }
;   if (__builtin_expect(__all(pmax - m_reg <= THR / SCALE), 1)) { mn = m_reg; alpha = 1.f; }
;   else { mn = fmaxf(m_reg, pmax); alpha = __builtin_amdgcn_exp2f((m_reg - mn) * C); m_reg = mn; }
;   const float mnC = -mn * C;
;     ...
;   float Cv = C; asm volatile("" : "+v"(Cv));
; #pragma unroll
;   for (int r = 0; r < 16; ++r) FMA_S(p0[r]);
; #pragma unroll
;   for (int r = 0; r < 16; ++r) FMA_S(p1[r]);
;     ...
; #pragma unroll
;   for (int r = 0; r < 16; ++r) p0[r] = __builtin_amdgcn_exp2f(p0[r]);
; }
; __device__ __forceinline__ void qkt3(f32x16& p0, f32x16& p1, const bf16x8* kf, const bf16x8* qr) {
;   p0 = f32x16{}; p1 = f32x16{};
; #pragma unroll
;   for (int d0 = 0; d0 < 6; ++d0) {
;     p0 = __builtin_amdgcn_mfma_f32_32x32x16_bf16(kf[2 * d0], qr[d0], p0, 0, 0, 0);
;     p1 = __builtin_amdgcn_mfma_f32_32x32x16_bf16(kf[2 * d0 + 1], qr[d0], p1, 0, 0, 0); }
; }
.Lpr_wd:
	s_and_b32 s62, s68, 0x3fffffc0
	s_lshl_b32 s62, s62, 2
	s_lshr_b32 s61, s22, 4
	s_and_b32 s61, s61, 7
	s_add_i32 s62, s62, 0x18000
	s_lshl_b32 s61, s61, 8
	s_barrier
	s_waitcnt lgkmcnt(0)
	v_mfma_f32_32x32x16_bf16 v[80:95], v[16:19], v[116:119], 0
	s_mov_b32 s68, 0
	s_mov_b32 s69, s68
	v_mfma_f32_32x32x16_bf16 v[80:95], v[68:71], v[112:115], v[80:95]
	s_mov_b32 s70, s68
	s_mov_b32 s71, s68
	v_mfma_f32_32x32x16_bf16 v[32:47], v[20:23], v[116:119], 0
	s_mov_b32 s72, s68
	s_mov_b32 s73, s68
	v_mfma_f32_32x32x16_bf16 v[80:95], v[60:63], v[108:111], v[80:95]
	s_mov_b32 s74, s68
	s_mov_b32 s75, s68
	v_mfma_f32_32x32x16_bf16 v[32:47], v[64:67], v[112:115], v[32:47]
	s_mov_b32 s76, s68
	s_mov_b32 s77, s68
	v_mfma_f32_32x32x16_bf16 v[80:95], v[12:15], v[104:107], v[80:95]
	s_mov_b32 s78, s68
	s_mov_b32 s79, s68
	v_mfma_f32_32x32x16_bf16 v[32:47], v[56:59], v[108:111], v[32:47]
	s_mov_b32 s80, s68
	s_mov_b32 s81, s68
	v_mfma_f32_32x32x16_bf16 v[80:95], v[4:7], v[100:103], v[80:95]
	s_mov_b32 s82, s68
	s_mov_b32 s83, s68
	v_mfma_f32_32x32x16_bf16 v[32:47], v[8:11], v[104:107], v[32:47]
	v_mfma_f32_32x32x16_bf16 v[80:95], v[0:3], v[96:99], v[80:95]
	v_mfma_f32_32x32x16_bf16 v[32:47], v[52:55], v[100:103], v[32:47]
	v_mfma_f32_32x32x16_bf16 v[32:47], v[48:51], v[96:99], v[32:47]
	s_nop 5
	v_mov_b64_e32 v[0:1], 0
	v_mov_b64_e32 v[2:3], 0
	v_mov_b64_e32 v[4:5], 0
	v_mov_b64_e32 v[6:7], 0
	v_mov_b64_e32 v[8:9], 0
	v_mov_b64_e32 v[10:11], 0
	v_mov_b64_e32 v[12:13], 0
	v_mov_b64_e32 v[14:15], 0
	v_max3_f32 v215, v80, v81, v82
	v_max3_f32 v215, v215, v83, v84
	v_max3_f32 v215, v215, v85, v86
	v_max3_f32 v215, v215, v87, v88
	v_max3_f32 v215, v215, v89, v90
	v_max3_f32 v215, v215, v91, v92
	v_max3_f32 v215, v215, v93, v94
	v_max3_f32 v215, v215, v95, v32
	v_max3_f32 v215, v215, v33, v34
	v_max3_f32 v215, v215, v35, v36
	v_max3_f32 v215, v215, v37, v38
	v_max3_f32 v215, v215, v39, v40
	v_max3_f32 v215, v215, v41, v42
	v_max3_f32 v215, v215, v43, v44
	v_max3_f32 v215, v215, v45, v46
	v_max_f32_e32 v215, v215, v47
	v_mov_b32_e32 v154, v215
	s_nop 1
	v_permlane32_swap_b32_e32 v215, v154
	v_max_f32_e32 v255, v215, v154
	v_sub_f32_e32 v238, 0, v255
	v_mov_b32_e32 v239, v238
	v_mov_b32_e32 v240, v238
	v_mov_b32_e32 v241, v238
	v_mov_b32_e32 v242, v238
	v_mov_b32_e32 v243, v238
	v_mov_b32_e32 v244, v238
	v_mov_b32_e32 v245, v238
	v_mov_b32_e32 v246, v238
	v_mov_b32_e32 v247, v238
	v_mov_b32_e32 v248, v238
	v_mov_b32_e32 v249, v238
	v_mov_b32_e32 v250, v238
	v_mov_b32_e32 v251, v238
	v_mov_b32_e32 v252, v238
	v_mov_b32_e32 v253, v238
	v_sub_f32_e32 v64, v32, v255
	v_sub_f32_e32 v65, v33, v255
	v_sub_f32_e32 v66, v34, v255
	v_sub_f32_e32 v67, v35, v255
	v_sub_f32_e32 v68, v36, v255
	v_sub_f32_e32 v69, v37, v255
	v_sub_f32_e32 v70, v38, v255
	v_sub_f32_e32 v71, v39, v255
	v_sub_f32_e32 v72, v40, v255
	v_sub_f32_e32 v73, v41, v255
	v_sub_f32_e32 v74, v42, v255
	v_sub_f32_e32 v75, v43, v255
	v_sub_f32_e32 v76, v44, v255
	v_sub_f32_e32 v77, v45, v255
	v_sub_f32_e32 v78, v46, v255
	v_sub_f32_e32 v79, v47, v255
	v_sub_f32_e32 v80, v80, v255
	v_sub_f32_e32 v81, v81, v255
	v_exp_f32_e32 v32, v80
	v_sub_f32_e32 v82, v82, v255
	v_exp_f32_e32 v33, v81
	v_sub_f32_e32 v83, v83, v255
	v_exp_f32_e32 v34, v82
	v_sub_f32_e32 v84, v84, v255
	v_exp_f32_e32 v35, v83
	v_sub_f32_e32 v85, v85, v255
	v_exp_f32_e32 v36, v84
	v_sub_f32_e32 v86, v86, v255
	v_exp_f32_e32 v37, v85
	v_sub_f32_e32 v87, v87, v255
	v_exp_f32_e32 v38, v86
	v_sub_f32_e32 v88, v88, v255
	v_exp_f32_e32 v39, v87
	v_sub_f32_e32 v89, v89, v255
	v_exp_f32_e32 v40, v88
	v_sub_f32_e32 v90, v90, v255
	v_exp_f32_e32 v41, v89
	v_sub_f32_e32 v91, v91, v255
	v_exp_f32_e32 v42, v90
	v_sub_f32_e32 v92, v92, v255
	v_exp_f32_e32 v43, v91
	v_sub_f32_e32 v93, v93, v255
	v_exp_f32_e32 v44, v92
	v_sub_f32_e32 v94, v94, v255
	v_exp_f32_e32 v45, v93
	v_sub_f32_e32 v95, v95, v255
	v_exp_f32_e32 v46, v94
	v_exp_f32_e32 v47, v95
	s_nop 0
	s_barrier
	s_lshl_b64 s[70:71], s[58:59], 18
	s_and_b32 s63, s84, 48
	s_or_b32 s70, s70, s63
	s_lshl_b64 s[58:59], s[58:59], 23
	v_lshl_add_u64 v[220:221], s[70:71], 0, v[200:201]
	s_add_u32 s70, s6, s61
	s_addc_u32 s71, 0, 0
	s_and_b32 s6, s84, 0x3ffffff0
	s_add_u32 s6, s6, s61
	v_or_b32_e32 v16, s58, v202
	v_add_u32_e32 v18, s60, v193
	s_addc_u32 s60, 0, 0
	v_mov_b32_e32 v17, s59
	v_lshl_or_b32 v16, v18, 11, v16
	s_add_u32 s58, s6, s58
	v_lshl_add_u64 v[222:223], s[70:71], 0, v[16:17]
	s_addc_u32 s59, s60, s59
	v_mov_b64_e32 v[30:31], v[14:15]
	v_lshl_add_u32 v211, v192, 2, s62
	v_lshl_add_u64 v[224:225], s[58:59], 0, v[204:205]
	v_mov_b32_e32 v213, 0
	s_mov_b32 s6, 1
	s_movk_i32 s70, 0x6000
	s_movk_i32 s69, 0x3000
	s_mov_b32 s63, 0x8000
	v_mov_b64_e32 v[28:29], v[12:13]
	v_mov_b64_e32 v[26:27], v[10:11]
	v_mov_b64_e32 v[24:25], v[8:9]
	v_mov_b64_e32 v[22:23], v[6:7]
	v_mov_b64_e32 v[20:21], v[4:5]
	v_mov_b64_e32 v[18:19], v[2:3]
	v_mov_b64_e32 v[16:17], v[0:1]
	s_mov_b32 s98, 0
	s_mov_b32 s99, 0x3000
	s_mov_b32 s100, 0x8000
	s_mov_b32 s101, 0
.LBB0_570:
	v_max3_f32 v215, v80, v81, v82
	v_max3_f32 v215, v215, v83, v84
	v_max3_f32 v215, v215, v85, v86
	v_max3_f32 v215, v215, v87, v88
	v_max3_f32 v215, v215, v89, v90
	v_max3_f32 v215, v215, v91, v92
	v_max3_f32 v215, v215, v93, v94
	v_max3_f32 v215, v215, v95, v64
	v_max3_f32 v215, v215, v65, v66
	v_max3_f32 v215, v215, v67, v68
	v_max3_f32 v215, v215, v69, v70
	v_max3_f32 v215, v215, v71, v72
	v_max3_f32 v215, v215, v73, v74
	v_max3_f32 v215, v215, v75, v76
	v_max3_f32 v215, v215, v77, v78
	v_max_f32_e32 v215, v215, v79
	v_cmp_nge_f32_e32 vcc, s23, v215
	s_nop 3
	s_cmp_lg_u64 vcc, 0
	s_cbranch_scc1 .Lrare_b

; __device__ __forceinline__ void finishSM2(f32x16& p0, f32x16& p1, float alpha, float& l_reg, bf16x8& pa0, bf16x8& pa1, bf16x8& pa2, bf16x8& pa3) {
; #pragma unroll
;   for (int r = 0; r < 16; ++r) p1[r] = __builtin_amdgcn_exp2f(p1[r]);
;   float ps = 0;
; #pragma unroll
;   for (int r = 0; r < 16; ++r) ps += p0[r];
; #pragma unroll
;   for (int r = 0; r < 16; ++r) ps += p1[r];
;   { auto rr = __builtin_amdgcn_permlane32_swap(__float_as_uint(ps), __float_as_uint(ps), false, false);
;     ps = __uint_as_float(rr[0]) + __uint_as_float(rr[1]); }
;   l_reg = l_reg * alpha + ps;
;     ...
;   PK8(p0, 0, pa0); PK8(p0, 8, pa1); PK8(p1, 0, pa2); PK8(p1, 8, pa3);
;     ...
; }
; __device__ __forceinline__ void kload12(bf16x8* kf, const LAS char* Ks, int r32, int hi) {
;   const LAS char* kb = Ks + hi * 1024 + r32 * 16;
; #pragma unroll
;   for (int d0 = 0; d0 < 6; ++d0) { kf[2 * d0] = *(const LAS bf16x8*)(kb + d0 * 2048); kf[2 * d0 + 1] = *(const LAS bf16x8*)(kb + d0 * 2048 + 512); }
; }
; __device__ __forceinline__ void qkt3(f32x16& p0, f32x16& p1, const bf16x8* kf, const bf16x8* qr) {
;   p0 = f32x16{}; p1 = f32x16{};
; #pragma unroll
;   for (int d0 = 0; d0 < 6; ++d0) {
;     p0 = __builtin_amdgcn_mfma_f32_32x32x16_bf16(kf[2 * d0], qr[d0], p0, 0, 0, 0);
;     p1 = __builtin_amdgcn_mfma_f32_32x32x16_bf16(kf[2 * d0 + 1], qr[d0], p1, 0, 0, 0); }
; }
; __device__ __forceinline__ void vload16(s16x4* vf, int vb) {
;   vf[0] = tr_read<0>(vb); vf[1] = tr_read<512>(vb); vf[2] = tr_read<1024>(vb); vf[3] = tr_read<1536>(vb);
;   vf[4] = tr_read<2048>(vb); vf[5] = tr_read<2560>(vb); vf[6] = tr_read<3072>(vb); vf[7] = tr_read<3584>(vb);
;   vf[8] = tr_read<4096>(vb); vf[9] = tr_read<4608>(vb); vf[10] = tr_read<5120>(vb); vf[11] = tr_read<5632>(vb);
;   vf[12] = tr_read<6144>(vb); vf[13] = tr_read<6656>(vb); vf[14] = tr_read<7168>(vb); vf[15] = tr_read<7680>(vb);
; }
; __device__ __forceinline__ void pv3(f32x16* o, const s16x4* vf, bf16x8 pa0, bf16x8 pa1, bf16x8 pa2, bf16x8 pa3) {
;     ...
;   o[0] = __builtin_amdgcn_mfma_f32_32x32x16_bf16(pa0, PKV(0), o[0], 0, 0, 0);
;   o[1] = __builtin_amdgcn_mfma_f32_32x32x16_bf16(pa0, PKV(8), o[1], 0, 0, 0);
;   o[0] = __builtin_amdgcn_mfma_f32_32x32x16_bf16(pa1, PKV(2), o[0], 0, 0, 0);
;   o[1] = __builtin_amdgcn_mfma_f32_32x32x16_bf16(pa1, PKV(10), o[1], 0, 0, 0);
;   o[0] = __builtin_amdgcn_mfma_f32_32x32x16_bf16(pa2, PKV(4), o[0], 0, 0, 0);
.Lwd_a:
	s_barrier
	s_waitcnt lgkmcnt(0)
	v_mfma_f32_32x32x16_bf16 v[80:95], v[48:51], v[116:119], v[238:253]
	v_exp_f32_e32 v64, v64
	v_add_f32_e32 v213, v32, v213
	ds_read_b64_tr_b16 v[148:149], v217 offset:0
	v_exp_f32_e32 v65, v65
	v_add_f32_e32 v213, v33, v213
	ds_read_b64_tr_b16 v[150:151], v217 offset:512
	v_mfma_f32_32x32x16_bf16 v[48:63], v[52:55], v[116:119], v[238:253]
	v_exp_f32_e32 v66, v66
	v_add_f32_e32 v213, v34, v213
	ds_read_b64_tr_b16 v[140:141], v217 offset:1024
	v_exp_f32_e32 v67, v67
	v_add_f32_e32 v213, v35, v213
	ds_read_b64_tr_b16 v[142:143], v217 offset:1536
	v_mfma_f32_32x32x16_bf16 v[80:95], v[188:191], v[112:115], v[80:95]
	v_exp_f32_e32 v68, v68
	v_add_f32_e32 v213, v36, v213
	ds_read_b64_tr_b16 v[132:133], v217 offset:2048
	v_exp_f32_e32 v69, v69
	v_add_f32_e32 v213, v37, v213
	ds_read_b64_tr_b16 v[134:135], v217 offset:2560
	v_mfma_f32_32x32x16_bf16 v[48:63], v[184:187], v[112:115], v[48:63]
	v_exp_f32_e32 v70, v70
	v_add_f32_e32 v213, v38, v213
	ds_read_b64_tr_b16 v[124:125], v217 offset:3072
	v_exp_f32_e32 v71, v71
	v_add_f32_e32 v213, v39, v213
	ds_read_b64_tr_b16 v[126:127], v217 offset:3584
	v_mfma_f32_32x32x16_bf16 v[80:95], v[180:183], v[108:111], v[80:95]
	v_exp_f32_e32 v72, v72
	v_add_f32_e32 v213, v40, v213
	ds_read_b64_tr_b16 v[144:145], v217 offset:4096
	v_exp_f32_e32 v73, v73
	v_add_f32_e32 v213, v41, v213
	ds_read_b64_tr_b16 v[146:147], v217 offset:4608
	v_mfma_f32_32x32x16_bf16 v[48:63], v[176:179], v[108:111], v[48:63]
	v_exp_f32_e32 v74, v74
	v_add_f32_e32 v213, v42, v213
	ds_read_b64_tr_b16 v[136:137], v217 offset:5120
	v_exp_f32_e32 v75, v75
	v_add_f32_e32 v213, v43, v213
	ds_read_b64_tr_b16 v[138:139], v217 offset:5632
	v_mfma_f32_32x32x16_bf16 v[80:95], v[172:175], v[104:107], v[80:95]
	v_exp_f32_e32 v76, v76
	v_add_f32_e32 v213, v44, v213
	ds_read_b64_tr_b16 v[128:129], v217 offset:6144
	v_exp_f32_e32 v77, v77
	v_add_f32_e32 v213, v45, v213
	ds_read_b64_tr_b16 v[130:131], v217 offset:6656
	v_mfma_f32_32x32x16_bf16 v[48:63], v[168:171], v[104:107], v[48:63]
	v_exp_f32_e32 v78, v78
	v_add_f32_e32 v213, v46, v213
	ds_read_b64_tr_b16 v[120:121], v217 offset:7168
	v_exp_f32_e32 v79, v79
	v_add_f32_e32 v213, v47, v213
	ds_read_b64_tr_b16 v[122:123], v217 offset:7680
	v_mfma_f32_32x32x16_bf16 v[80:95], v[164:167], v[100:103], v[80:95]
	v_add_f32_e32 v237, v64, v65
	v_add_f32_e32 v237, v66, v237
	v_add_f32_e32 v237, v67, v237
	v_add_f32_e32 v237, v68, v237
	v_add_f32_e32 v237, v69, v237
	v_add_f32_e32 v237, v70, v237
	v_add_f32_e32 v237, v71, v237
	v_add_f32_e32 v237, v72, v237
	v_mfma_f32_32x32x16_bf16 v[48:63], v[160:163], v[100:103], v[48:63]
	v_add_f32_e32 v237, v73, v237
	v_add_f32_e32 v237, v74, v237
	v_add_f32_e32 v237, v75, v237
	v_add_f32_e32 v237, v76, v237
	v_add_f32_e32 v237, v77, v237
	v_add_f32_e32 v237, v78, v237
	v_add_f32_e32 v237, v79, v237
	v_add_f32_e32 v213, v237, v213
	v_mfma_f32_32x32x16_bf16 v[80:95], v[156:159], v[96:99], v[80:95]
	v_cvt_pk_bf16_f32 v32, v32, v33
	v_cvt_pk_bf16_f32 v33, v34, v35
	v_cvt_pk_bf16_f32 v34, v36, v37
	v_cvt_pk_bf16_f32 v35, v38, v39
	v_cvt_pk_bf16_f32 v36, v40, v41
	v_cvt_pk_bf16_f32 v37, v42, v43
	v_cvt_pk_bf16_f32 v38, v44, v45
	v_cvt_pk_bf16_f32 v39, v46, v47
	v_mfma_f32_32x32x16_bf16 v[48:63], v[152:155], v[96:99], v[48:63]
	v_cvt_pk_bf16_f32 v64, v64, v65
	v_cvt_pk_bf16_f32 v65, v66, v67
	v_cvt_pk_bf16_f32 v66, v68, v69
	v_cvt_pk_bf16_f32 v67, v70, v71
	v_cvt_pk_bf16_f32 v68, v72, v73
	v_cvt_pk_bf16_f32 v69, v74, v75
	v_cvt_pk_bf16_f32 v70, v76, v77
	v_cvt_pk_bf16_f32 v71, v78, v79
	s_waitcnt lgkmcnt(0)
	v_mfma_f32_32x32x16_bf16 v[0:15], v[32:35], v[148:151], v[0:15]
	v_exp_f32_e32 v40, v88
	v_exp_f32_e32 v41, v89
	v_mfma_f32_32x32x16_bf16 v[16:31], v[32:35], v[144:147], v[16:31]
	v_exp_f32_e32 v42, v90
	v_exp_f32_e32 v43, v91
	v_mfma_f32_32x32x16_bf16 v[0:15], v[36:39], v[140:143], v[0:15]
	v_exp_f32_e32 v44, v92
	v_exp_f32_e32 v45, v93
	v_mfma_f32_32x32x16_bf16 v[16:31], v[36:39], v[136:139], v[16:31]
	v_exp_f32_e32 v46, v94
	v_exp_f32_e32 v47, v95
	v_mfma_f32_32x32x16_bf16 v[0:15], v[64:67], v[132:135], v[0:15]
	v_exp_f32_e32 v32, v80
	v_exp_f32_e32 v33, v81
	v_mfma_f32_32x32x16_bf16 v[16:31], v[64:67], v[128:131], v[16:31]
	v_exp_f32_e32 v34, v82
	v_exp_f32_e32 v35, v83
	v_mfma_f32_32x32x16_bf16 v[0:15], v[68:71], v[124:127], v[0:15]
	v_exp_f32_e32 v36, v84
	v_exp_f32_e32 v37, v85
	v_mfma_f32_32x32x16_bf16 v[16:31], v[68:71], v[120:123], v[16:31]
	v_exp_f32_e32 v38, v86
	v_exp_f32_e32 v39, v87
	s_barrier
	v_max3_f32 v215, v80, v81, v82
	v_max3_f32 v215, v215, v83, v84
	v_max3_f32 v215, v215, v85, v86
	v_max3_f32 v215, v215, v87, v88
	v_max3_f32 v215, v215, v89, v90
	v_max3_f32 v215, v215, v91, v92
	v_max3_f32 v215, v215, v93, v94
	v_max3_f32 v215, v215, v95, v48
	v_max3_f32 v215, v215, v49, v50
	v_max3_f32 v215, v215, v51, v52
	v_max3_f32 v215, v215, v53, v54
	v_max3_f32 v215, v215, v55, v56
	v_max3_f32 v215, v215, v57, v58
	v_max3_f32 v215, v215, v59, v60
	v_max3_f32 v215, v215, v61, v62
	v_max_f32_e32 v215, v215, v63
	v_cmp_nge_f32_e32 vcc, s23, v215
	s_nop 3
	s_cmp_lg_u64 vcc, 0
	s_cbranch_scc1 .Lrare_a

; __device__ __forceinline__ void finishSM2(f32x16& p0, f32x16& p1, float alpha, float& l_reg, bf16x8& pa0, bf16x8& pa1, bf16x8& pa2, bf16x8& pa3) {
; #pragma unroll
;   for (int r = 0; r < 16; ++r) p1[r] = __builtin_amdgcn_exp2f(p1[r]);
;   float ps = 0;
; #pragma unroll
;   for (int r = 0; r < 16; ++r) ps += p0[r];
; #pragma unroll
;   for (int r = 0; r < 16; ++r) ps += p1[r];
;   { auto rr = __builtin_amdgcn_permlane32_swap(__float_as_uint(ps), __float_as_uint(ps), false, false);
;     ps = __uint_as_float(rr[0]) + __uint_as_float(rr[1]); }
;   l_reg = l_reg * alpha + ps;
;     ...
;   PK8(p0, 0, pa0); PK8(p0, 8, pa1); PK8(p1, 0, pa2); PK8(p1, 8, pa3);
;     ...
; }
; __device__ __forceinline__ void kload12(bf16x8* kf, const LAS char* Ks, int r32, int hi) {
;   const LAS char* kb = Ks + hi * 1024 + r32 * 16;
; #pragma unroll
;   for (int d0 = 0; d0 < 6; ++d0) { kf[2 * d0] = *(const LAS bf16x8*)(kb + d0 * 2048); kf[2 * d0 + 1] = *(const LAS bf16x8*)(kb + d0 * 2048 + 512); }
; }
; __device__ __forceinline__ void qkt3(f32x16& p0, f32x16& p1, const bf16x8* kf, const bf16x8* qr) {
;   p0 = f32x16{}; p1 = f32x16{};
; #pragma unroll
;   for (int d0 = 0; d0 < 6; ++d0) {
;     p0 = __builtin_amdgcn_mfma_f32_32x32x16_bf16(kf[2 * d0], qr[d0], p0, 0, 0, 0);
;     p1 = __builtin_amdgcn_mfma_f32_32x32x16_bf16(kf[2 * d0 + 1], qr[d0], p1, 0, 0, 0); }
; }
; __device__ __forceinline__ void vload16(s16x4* vf, int vb) {
;   vf[0] = tr_read<0>(vb); vf[1] = tr_read<512>(vb); vf[2] = tr_read<1024>(vb); vf[3] = tr_read<1536>(vb);
;   vf[4] = tr_read<2048>(vb); vf[5] = tr_read<2560>(vb); vf[6] = tr_read<3072>(vb); vf[7] = tr_read<3584>(vb);
;   vf[8] = tr_read<4096>(vb); vf[9] = tr_read<4608>(vb); vf[10] = tr_read<5120>(vb); vf[11] = tr_read<5632>(vb);
;   vf[12] = tr_read<6144>(vb); vf[13] = tr_read<6656>(vb); vf[14] = tr_read<7168>(vb); vf[15] = tr_read<7680>(vb);
; }
; __device__ __forceinline__ void pv3(f32x16* o, const s16x4* vf, bf16x8 pa0, bf16x8 pa1, bf16x8 pa2, bf16x8 pa3) {
;     ...
;   o[0] = __builtin_amdgcn_mfma_f32_32x32x16_bf16(pa0, PKV(0), o[0], 0, 0, 0);
;   o[1] = __builtin_amdgcn_mfma_f32_32x32x16_bf16(pa0, PKV(8), o[1], 0, 0, 0);
;   o[0] = __builtin_amdgcn_mfma_f32_32x32x16_bf16(pa1, PKV(2), o[0], 0, 0, 0);
;   o[1] = __builtin_amdgcn_mfma_f32_32x32x16_bf16(pa1, PKV(10), o[1], 0, 0, 0);
;   o[0] = __builtin_amdgcn_mfma_f32_32x32x16_bf16(pa2, PKV(4), o[0], 0, 0, 0);
.Lwd_b:
	s_barrier
	s_waitcnt lgkmcnt(0)
	v_mfma_f32_32x32x16_bf16 v[80:95], v[64:67], v[116:119], v[238:253]
	v_exp_f32_e32 v48, v48
	v_add_f32_e32 v213, v32, v213
	ds_read_b64_tr_b16 v[148:149], v217 offset:0
	v_exp_f32_e32 v49, v49
	v_add_f32_e32 v213, v33, v213
	ds_read_b64_tr_b16 v[150:151], v217 offset:512
	v_mfma_f32_32x32x16_bf16 v[64:79], v[68:71], v[116:119], v[238:253]
	v_exp_f32_e32 v50, v50
	v_add_f32_e32 v213, v34, v213
	ds_read_b64_tr_b16 v[140:141], v217 offset:1024
	v_exp_f32_e32 v51, v51
	v_add_f32_e32 v213, v35, v213
	ds_read_b64_tr_b16 v[142:143], v217 offset:1536
	v_mfma_f32_32x32x16_bf16 v[80:95], v[188:191], v[112:115], v[80:95]
	v_exp_f32_e32 v52, v52
	v_add_f32_e32 v213, v36, v213
	ds_read_b64_tr_b16 v[132:133], v217 offset:2048
	v_exp_f32_e32 v53, v53
	v_add_f32_e32 v213, v37, v213
	ds_read_b64_tr_b16 v[134:135], v217 offset:2560
	v_mfma_f32_32x32x16_bf16 v[64:79], v[184:187], v[112:115], v[64:79]
	v_exp_f32_e32 v54, v54
	v_add_f32_e32 v213, v38, v213
	ds_read_b64_tr_b16 v[124:125], v217 offset:3072
	v_exp_f32_e32 v55, v55
	v_add_f32_e32 v213, v39, v213
	ds_read_b64_tr_b16 v[126:127], v217 offset:3584
	v_mfma_f32_32x32x16_bf16 v[80:95], v[180:183], v[108:111], v[80:95]
	v_exp_f32_e32 v56, v56
	v_add_f32_e32 v213, v40, v213
	ds_read_b64_tr_b16 v[144:145], v217 offset:4096
	v_exp_f32_e32 v57, v57
	v_add_f32_e32 v213, v41, v213
	ds_read_b64_tr_b16 v[146:147], v217 offset:4608
	v_mfma_f32_32x32x16_bf16 v[64:79], v[176:179], v[108:111], v[64:79]
	v_exp_f32_e32 v58, v58
	v_add_f32_e32 v213, v42, v213
	ds_read_b64_tr_b16 v[136:137], v217 offset:5120
	v_exp_f32_e32 v59, v59
	v_add_f32_e32 v213, v43, v213
	ds_read_b64_tr_b16 v[138:139], v217 offset:5632
	v_mfma_f32_32x32x16_bf16 v[80:95], v[172:175], v[104:107], v[80:95]
	v_exp_f32_e32 v60, v60
	v_add_f32_e32 v213, v44, v213
	ds_read_b64_tr_b16 v[128:129], v217 offset:6144
	v_exp_f32_e32 v61, v61
	v_add_f32_e32 v213, v45, v213
	ds_read_b64_tr_b16 v[130:131], v217 offset:6656
	v_mfma_f32_32x32x16_bf16 v[64:79], v[168:171], v[104:107], v[64:79]
	v_exp_f32_e32 v62, v62
	v_add_f32_e32 v213, v46, v213
	ds_read_b64_tr_b16 v[120:121], v217 offset:7168
	v_exp_f32_e32 v63, v63
	v_add_f32_e32 v213, v47, v213
	ds_read_b64_tr_b16 v[122:123], v217 offset:7680
	v_mfma_f32_32x32x16_bf16 v[80:95], v[164:167], v[100:103], v[80:95]
	v_add_f32_e32 v237, v48, v49
	v_add_f32_e32 v237, v50, v237
	v_add_f32_e32 v237, v51, v237
	v_add_f32_e32 v237, v52, v237
	v_add_f32_e32 v237, v53, v237
	v_add_f32_e32 v237, v54, v237
	v_add_f32_e32 v237, v55, v237
	v_add_f32_e32 v237, v56, v237
	v_mfma_f32_32x32x16_bf16 v[64:79], v[160:163], v[100:103], v[64:79]
	v_add_f32_e32 v237, v57, v237
	v_add_f32_e32 v237, v58, v237
	v_add_f32_e32 v237, v59, v237
	v_add_f32_e32 v237, v60, v237
	v_add_f32_e32 v237, v61, v237
	v_add_f32_e32 v237, v62, v237
	v_add_f32_e32 v237, v63, v237
	v_add_f32_e32 v213, v237, v213
	v_mfma_f32_32x32x16_bf16 v[80:95], v[156:159], v[96:99], v[80:95]
	v_cvt_pk_bf16_f32 v32, v32, v33
	v_cvt_pk_bf16_f32 v33, v34, v35
	v_cvt_pk_bf16_f32 v34, v36, v37
	v_cvt_pk_bf16_f32 v35, v38, v39
	v_cvt_pk_bf16_f32 v36, v40, v41
	v_cvt_pk_bf16_f32 v37, v42, v43
	v_cvt_pk_bf16_f32 v38, v44, v45
	v_cvt_pk_bf16_f32 v39, v46, v47
	v_mfma_f32_32x32x16_bf16 v[64:79], v[152:155], v[96:99], v[64:79]
	v_cvt_pk_bf16_f32 v48, v48, v49
	v_cvt_pk_bf16_f32 v49, v50, v51
	v_cvt_pk_bf16_f32 v50, v52, v53
	v_cvt_pk_bf16_f32 v51, v54, v55
	v_cvt_pk_bf16_f32 v52, v56, v57
	v_cvt_pk_bf16_f32 v53, v58, v59
	v_cvt_pk_bf16_f32 v54, v60, v61
	v_cvt_pk_bf16_f32 v55, v62, v63
	s_waitcnt lgkmcnt(0)
	v_mfma_f32_32x32x16_bf16 v[0:15], v[32:35], v[148:151], v[0:15]
	v_exp_f32_e32 v40, v88
	v_exp_f32_e32 v41, v89
	v_mfma_f32_32x32x16_bf16 v[16:31], v[32:35], v[144:147], v[16:31]
	v_exp_f32_e32 v42, v90
	v_exp_f32_e32 v43, v91
	v_mfma_f32_32x32x16_bf16 v[0:15], v[36:39], v[140:143], v[0:15]
	v_exp_f32_e32 v44, v92
	v_exp_f32_e32 v45, v93
	v_mfma_f32_32x32x16_bf16 v[16:31], v[36:39], v[136:139], v[16:31]
	v_exp_f32_e32 v46, v94
	v_exp_f32_e32 v47, v95
	v_mfma_f32_32x32x16_bf16 v[0:15], v[48:51], v[132:135], v[0:15]
	v_exp_f32_e32 v32, v80
	v_exp_f32_e32 v33, v81
	v_mfma_f32_32x32x16_bf16 v[16:31], v[48:51], v[128:131], v[16:31]
	v_exp_f32_e32 v34, v82
	v_exp_f32_e32 v35, v83
	v_mfma_f32_32x32x16_bf16 v[0:15], v[52:55], v[124:127], v[0:15]
	v_exp_f32_e32 v36, v84
	v_exp_f32_e32 v37, v85
	v_mfma_f32_32x32x16_bf16 v[16:31], v[52:55], v[120:123], v[16:31]
	v_exp_f32_e32 v38, v86
	v_exp_f32_e32 v39, v87
	s_add_i32 s6, s6, 2
	s_barrier
	s_addk_i32 s63, 0x4000
	v_lshl_add_u64 v[220:221], v[220:221], 0, s[12:13]
	v_lshl_add_u64 v[222:223], v[222:223], 0, s[10:11]
	v_lshl_add_u64 v[224:225], v[224:225], 0, s[10:11]
	s_and_b64 vcc, exec, s[58:59]
	s_cbranch_vccnz .LBB0_597
	s_mov_b32 s68, s70
	s_mov_b32 s70, s71
	s_branch .LBB0_570

; __device__ __forceinline__ void finishSM2(f32x16& p0, f32x16& p1, float alpha, float& l_reg, bf16x8& pa0, bf16x8& pa1, bf16x8& pa2, bf16x8& pa3) {
; #pragma unroll
;   for (int r = 0; r < 16; ++r) p1[r] = __builtin_amdgcn_exp2f(p1[r]);
;   float ps = 0;
; #pragma unroll
;   for (int r = 0; r < 16; ++r) ps += p0[r];
; #pragma unroll
;   for (int r = 0; r < 16; ++r) ps += p1[r];
;   { auto rr = __builtin_amdgcn_permlane32_swap(__float_as_uint(ps), __float_as_uint(ps), false, false);
;     ps = __uint_as_float(rr[0]) + __uint_as_float(rr[1]); }
;   l_reg = l_reg * alpha + ps;
;     ...
;   PK8(p0, 0, pa0); PK8(p0, 8, pa1); PK8(p1, 0, pa2); PK8(p1, 8, pa3);
;     ...
; }
; __device__ __forceinline__ void kload12(bf16x8* kf, const LAS char* Ks, int r32, int hi) {
;   const LAS char* kb = Ks + hi * 1024 + r32 * 16;
; #pragma unroll
;   for (int d0 = 0; d0 < 6; ++d0) { kf[2 * d0] = *(const LAS bf16x8*)(kb + d0 * 2048); kf[2 * d0 + 1] = *(const LAS bf16x8*)(kb + d0 * 2048 + 512); }
; }
; __device__ __forceinline__ void qkt3(f32x16& p0, f32x16& p1, const bf16x8* kf, const bf16x8* qr) {
;   p0 = f32x16{}; p1 = f32x16{};
; #pragma unroll
;   for (int d0 = 0; d0 < 6; ++d0) {
;     p0 = __builtin_amdgcn_mfma_f32_32x32x16_bf16(kf[2 * d0], qr[d0], p0, 0, 0, 0);
;     p1 = __builtin_amdgcn_mfma_f32_32x32x16_bf16(kf[2 * d0 + 1], qr[d0], p1, 0, 0, 0); }
; }
; __device__ __forceinline__ void vload16(s16x4* vf, int vb) {
;   vf[0] = tr_read<0>(vb); vf[1] = tr_read<512>(vb); vf[2] = tr_read<1024>(vb); vf[3] = tr_read<1536>(vb);
;   vf[4] = tr_read<2048>(vb); vf[5] = tr_read<2560>(vb); vf[6] = tr_read<3072>(vb); vf[7] = tr_read<3584>(vb);
;   vf[8] = tr_read<4096>(vb); vf[9] = tr_read<4608>(vb); vf[10] = tr_read<5120>(vb); vf[11] = tr_read<5632>(vb);
;   vf[12] = tr_read<6144>(vb); vf[13] = tr_read<6656>(vb); vf[14] = tr_read<7168>(vb); vf[15] = tr_read<7680>(vb);
; }
; __device__ __forceinline__ void pv3(f32x16* o, const s16x4* vf, bf16x8 pa0, bf16x8 pa1, bf16x8 pa2, bf16x8 pa3) {
;     ...
;   o[0] = __builtin_amdgcn_mfma_f32_32x32x16_bf16(pa0, PKV(0), o[0], 0, 0, 0);
;   o[1] = __builtin_amdgcn_mfma_f32_32x32x16_bf16(pa0, PKV(8), o[1], 0, 0, 0);
;   o[0] = __builtin_amdgcn_mfma_f32_32x32x16_bf16(pa1, PKV(2), o[0], 0, 0, 0);
;   o[1] = __builtin_amdgcn_mfma_f32_32x32x16_bf16(pa1, PKV(10), o[1], 0, 0, 0);
;   o[0] = __builtin_amdgcn_mfma_f32_32x32x16_bf16(pa2, PKV(4), o[0], 0, 0, 0);
.Ljoin_u:
	ds_read_b128 v[48:51], v231 offset:36864
	ds_read_b128 v[52:55], v231 offset:37376
	ds_read_b128 v[188:191], v231 offset:38912
	ds_read_b128 v[184:187], v231 offset:39424
	ds_read_b128 v[180:183], v231 offset:40960
	ds_read_b128 v[176:179], v231 offset:41472
	ds_read_b128 v[172:175], v231 offset:43008
	ds_read_b128 v[168:171], v231 offset:43520
	ds_read_b128 v[164:167], v231 offset:45056
	ds_read_b128 v[160:163], v231 offset:45568
	ds_read_b128 v[156:159], v231 offset:47104
	ds_read_b128 v[152:155], v231 offset:47616
	s_waitcnt vmcnt(0) lgkmcnt(0)
	s_barrier
	s_waitcnt lgkmcnt(0)
	v_mfma_f32_32x32x16_bf16 v[80:95], v[48:51], v[116:119], v[238:253]
	v_exp_f32_e32 v64, v64
	v_add_f32_e32 v213, v32, v213
	ds_read_b64_tr_b16 v[148:149], v233 offset:0
	v_exp_f32_e32 v65, v65
	v_add_f32_e32 v213, v33, v213
	ds_read_b64_tr_b16 v[150:151], v233 offset:512
	v_mfma_f32_32x32x16_bf16 v[48:63], v[52:55], v[116:119], v[238:253]
	v_exp_f32_e32 v66, v66
	v_add_f32_e32 v213, v34, v213
	ds_read_b64_tr_b16 v[140:141], v233 offset:1024
	v_exp_f32_e32 v67, v67
	v_add_f32_e32 v213, v35, v213
	ds_read_b64_tr_b16 v[142:143], v233 offset:1536
	v_mfma_f32_32x32x16_bf16 v[80:95], v[188:191], v[112:115], v[80:95]
	v_exp_f32_e32 v68, v68
	v_add_f32_e32 v213, v36, v213
	ds_read_b64_tr_b16 v[132:133], v233 offset:2048
	v_exp_f32_e32 v69, v69
	v_add_f32_e32 v213, v37, v213
	ds_read_b64_tr_b16 v[134:135], v233 offset:2560
	v_mfma_f32_32x32x16_bf16 v[48:63], v[184:187], v[112:115], v[48:63]
	v_exp_f32_e32 v70, v70
	v_add_f32_e32 v213, v38, v213
	ds_read_b64_tr_b16 v[124:125], v233 offset:3072
	v_exp_f32_e32 v71, v71
	v_add_f32_e32 v213, v39, v213
	ds_read_b64_tr_b16 v[126:127], v233 offset:3584
	v_mfma_f32_32x32x16_bf16 v[80:95], v[180:183], v[108:111], v[80:95]
	v_exp_f32_e32 v72, v72
	v_add_f32_e32 v213, v40, v213
	ds_read_b64_tr_b16 v[144:145], v233 offset:4096
	v_exp_f32_e32 v73, v73
	v_add_f32_e32 v213, v41, v213
	ds_read_b64_tr_b16 v[146:147], v233 offset:4608
	v_mfma_f32_32x32x16_bf16 v[48:63], v[176:179], v[108:111], v[48:63]
	v_exp_f32_e32 v74, v74
	v_add_f32_e32 v213, v42, v213
	ds_read_b64_tr_b16 v[136:137], v233 offset:5120
	v_exp_f32_e32 v75, v75
	v_add_f32_e32 v213, v43, v213
	ds_read_b64_tr_b16 v[138:139], v233 offset:5632
	v_mfma_f32_32x32x16_bf16 v[80:95], v[172:175], v[104:107], v[80:95]
	v_exp_f32_e32 v76, v76
	v_add_f32_e32 v213, v44, v213
	ds_read_b64_tr_b16 v[128:129], v233 offset:6144
	v_exp_f32_e32 v77, v77
	v_add_f32_e32 v213, v45, v213
	ds_read_b64_tr_b16 v[130:131], v233 offset:6656
	v_mfma_f32_32x32x16_bf16 v[48:63], v[168:171], v[104:107], v[48:63]
	v_exp_f32_e32 v78, v78
	v_add_f32_e32 v213, v46, v213
	ds_read_b64_tr_b16 v[120:121], v233 offset:7168
	v_exp_f32_e32 v79, v79
	v_add_f32_e32 v213, v47, v213
	ds_read_b64_tr_b16 v[122:123], v233 offset:7680
	v_mfma_f32_32x32x16_bf16 v[80:95], v[164:167], v[100:103], v[80:95]
	v_add_f32_e32 v237, v64, v65
	v_add_f32_e32 v237, v66, v237
	v_add_f32_e32 v237, v67, v237
	v_add_f32_e32 v237, v68, v237
	v_add_f32_e32 v237, v69, v237
	v_add_f32_e32 v237, v70, v237
	v_add_f32_e32 v237, v71, v237
	v_add_f32_e32 v237, v72, v237
	v_mfma_f32_32x32x16_bf16 v[48:63], v[160:163], v[100:103], v[48:63]
	v_add_f32_e32 v237, v73, v237
	v_add_f32_e32 v237, v74, v237
	v_add_f32_e32 v237, v75, v237
	v_add_f32_e32 v237, v76, v237
	v_add_f32_e32 v237, v77, v237
	v_add_f32_e32 v237, v78, v237
	v_add_f32_e32 v237, v79, v237
	v_add_f32_e32 v213, v237, v213
	v_mfma_f32_32x32x16_bf16 v[80:95], v[156:159], v[96:99], v[80:95]
	v_cvt_pk_bf16_f32 v32, v32, v33
	v_cvt_pk_bf16_f32 v33, v34, v35
	v_cvt_pk_bf16_f32 v34, v36, v37
	v_cvt_pk_bf16_f32 v35, v38, v39
	v_cvt_pk_bf16_f32 v36, v40, v41
	v_cvt_pk_bf16_f32 v37, v42, v43
	v_cvt_pk_bf16_f32 v38, v44, v45
	v_cvt_pk_bf16_f32 v39, v46, v47
	v_mfma_f32_32x32x16_bf16 v[48:63], v[152:155], v[96:99], v[48:63]
	v_cvt_pk_bf16_f32 v64, v64, v65
	v_cvt_pk_bf16_f32 v65, v66, v67
	v_cvt_pk_bf16_f32 v66, v68, v69
	v_cvt_pk_bf16_f32 v67, v70, v71
	v_cvt_pk_bf16_f32 v68, v72, v73
	v_cvt_pk_bf16_f32 v69, v74, v75
	v_cvt_pk_bf16_f32 v70, v76, v77
	v_cvt_pk_bf16_f32 v71, v78, v79
	s_waitcnt lgkmcnt(0)
	v_mfma_f32_32x32x16_bf16 v[0:15], v[32:35], v[148:151], v[0:15]
	v_exp_f32_e32 v40, v88
	v_exp_f32_e32 v41, v89
	v_mfma_f32_32x32x16_bf16 v[16:31], v[32:35], v[144:147], v[16:31]
	v_exp_f32_e32 v42, v90
	v_exp_f32_e32 v43, v91
	v_mfma_f32_32x32x16_bf16 v[0:15], v[36:39], v[140:143], v[0:15]
	v_exp_f32_e32 v44, v92
	v_exp_f32_e32 v45, v93
	v_mfma_f32_32x32x16_bf16 v[16:31], v[36:39], v[136:139], v[16:31]
	v_exp_f32_e32 v46, v94
	v_exp_f32_e32 v47, v95
	v_mfma_f32_32x32x16_bf16 v[0:15], v[64:67], v[132:135], v[0:15]
	v_exp_f32_e32 v32, v80
	v_exp_f32_e32 v33, v81
	v_mfma_f32_32x32x16_bf16 v[16:31], v[64:67], v[128:131], v[16:31]
	v_exp_f32_e32 v34, v82
	v_exp_f32_e32 v35, v83
	v_mfma_f32_32x32x16_bf16 v[0:15], v[68:71], v[124:127], v[0:15]
	v_exp_f32_e32 v36, v84
	v_exp_f32_e32 v37, v85
	v_mfma_f32_32x32x16_bf16 v[16:31], v[68:71], v[120:123], v[16:31]
	v_exp_f32_e32 v38, v86
	v_exp_f32_e32 v39, v87
	s_barrier
	s_and_b64 vcc, exec, s[4:5]
	s_cbranch_vccnz .LBB0_603
	s_barrier
.LBB0_603:
	v_max3_f32 v215, v80, v81, v82
	v_max3_f32 v215, v215, v83, v84
	v_max3_f32 v215, v215, v85, v86
	v_max3_f32 v215, v215, v87, v88
	v_max3_f32 v215, v215, v89, v90
	v_max3_f32 v215, v215, v91, v92
	v_max3_f32 v215, v215, v93, v94
	v_max3_f32 v215, v215, v95, v48
	v_max3_f32 v215, v215, v49, v50
	v_max3_f32 v215, v215, v51, v52
	v_max3_f32 v215, v215, v53, v54
	v_max3_f32 v215, v215, v55, v56
	v_max3_f32 v215, v215, v57, v58
	v_max3_f32 v215, v215, v59, v60
	v_max3_f32 v215, v215, v61, v62
	v_max_f32_e32 v215, v215, v63
	v_cmp_nge_f32_e32 vcc, s23, v215
	s_nop 3
	s_cmp_lg_u64 vcc, 0
	s_cbranch_scc1 .Lrare_t
; #define FMA_S(x) asm("v_fma_f32 %0, %1, %2, %3" : "=v"(x) : "v"(x), "v"(Cv), "v"(mnC))
; #define PK8(P, B, OUT) do { u32x4 w = {cvt_pk_bf16(P[B + 0], P[B + 1]), cvt_pk_bf16(P[B + 2], P[B + 3]), cvt_pk_bf16(P[B + 4], P[B + 5]), cvt_pk_bf16(P[B + 6], P[B + 7])}; OUT = *reinterpret_cast<bf16x8*>(&w); } while (0)
; #define PK8(P, B, OUT) do { u32x4 w = {cvt_pk_bf16(P[B + 0], P[B + 1]), cvt_pk_bf16(P[B + 2], P[B + 3]), cvt_pk_bf16(P[B + 4], P[B + 5]), cvt_pk_bf16(P[B + 6], P[B + 7])}; OUT = *reinterpret_cast<bf16x8*>(&w); } while (0)
; __device__ __forceinline__ void partialSM(f32x16& p0, f32x16& p1, float& m_reg, float& mn, float& alpha) {
;   constexpr float C = SCALE * 1.4426950408889634f;
;   float pmax = p0[0];
; #pragma unroll
;   for (int r = 1; r < 16; ++r) pmax = fmaxf(pmax, p0[r]);
; #pragma unroll
;   for (int r = 0; r < 16; ++r) pmax = fmaxf(pmax, p1[r]);
;   { auto rr = __builtin_amdgcn_permlane32_swap(__float_as_uint(pmax), __float_as_uint(pmax), false, false);
;     pmax = fmaxf(__uint_as_float(rr[0]), __uint_as_float(rr[1])); }
;   if (__builtin_expect(__all(pmax - m_reg <= THR / SCALE), 1)) { mn = m_reg; alpha = 1.f; }
;   else { mn = fmaxf(m_reg, pmax); alpha = __builtin_amdgcn_exp2f((m_reg - mn) * C); m_reg = mn; }
;   const float mnC = -mn * C;
;     ...
;   float Cv = C; asm volatile("" : "+v"(Cv));
; #pragma unroll
;   for (int r = 0; r < 16; ++r) FMA_S(p0[r]);
; #pragma unroll
;   for (int r = 0; r < 16; ++r) FMA_S(p1[r]);
;     ...
; #pragma unroll
;   for (int r = 0; r < 16; ++r) p0[r] = __builtin_amdgcn_exp2f(p0[r]);
; }
; __device__ __forceinline__ void finishSM2(f32x16& p0, f32x16& p1, float alpha, float& l_reg, bf16x8& pa0, bf16x8& pa1, bf16x8& pa2, bf16x8& pa3) {
; #pragma unroll
;   for (int r = 0; r < 16; ++r) p1[r] = __builtin_amdgcn_exp2f(p1[r]);
;   float ps = 0;
; #pragma unroll
;   for (int r = 0; r < 16; ++r) ps += p0[r];
; #pragma unroll
;   for (int r = 0; r < 16; ++r) ps += p1[r];
;   { auto rr = __builtin_amdgcn_permlane32_swap(__float_as_uint(ps), __float_as_uint(ps), false, false);
;     ps = __uint_as_float(rr[0]) + __uint_as_float(rr[1]); }
;   l_reg = l_reg * alpha + ps;
;     ...
;   PK8(p0, 0, pa0); PK8(p0, 8, pa1); PK8(p1, 0, pa2); PK8(p1, 8, pa3);
;     ...
; }
.Ljoin_t:
	ds_read_b64_tr_b16 v[64:65], v234 offset:0
	ds_read_b64_tr_b16 v[66:67], v234 offset:512
	ds_read_b64_tr_b16 v[68:69], v234 offset:1024
	ds_read_b64_tr_b16 v[70:71], v234 offset:1536
	ds_read_b64_tr_b16 v[72:73], v234 offset:2048
	ds_read_b64_tr_b16 v[74:75], v234 offset:2560
	ds_read_b64_tr_b16 v[76:77], v234 offset:3072
	ds_read_b64_tr_b16 v[78:79], v234 offset:3584
	ds_read_b64_tr_b16 v[80:81], v234 offset:4096
	ds_read_b64_tr_b16 v[82:83], v234 offset:4608
	ds_read_b64_tr_b16 v[84:85], v234 offset:5120
	ds_read_b64_tr_b16 v[86:87], v234 offset:5632
	ds_read_b64_tr_b16 v[88:89], v234 offset:6144
	ds_read_b64_tr_b16 v[90:91], v234 offset:6656
	ds_read_b64_tr_b16 v[92:93], v234 offset:7168
	ds_read_b64_tr_b16 v[94:95], v234 offset:7680
	v_exp_f32_e32 v48, v48
	v_add_f32_e32 v213, v32, v213
	v_exp_f32_e32 v49, v49
	v_add_f32_e32 v213, v33, v213
	v_exp_f32_e32 v50, v50
	v_add_f32_e32 v213, v34, v213
	v_exp_f32_e32 v51, v51
	v_add_f32_e32 v213, v35, v213
	v_exp_f32_e32 v52, v52
	v_add_f32_e32 v213, v36, v213
	v_exp_f32_e32 v53, v53
	v_add_f32_e32 v213, v37, v213
	v_exp_f32_e32 v54, v54
	v_add_f32_e32 v213, v38, v213
	v_exp_f32_e32 v55, v55
	v_add_f32_e32 v213, v39, v213
	v_exp_f32_e32 v56, v56
	v_add_f32_e32 v213, v40, v213
	v_exp_f32_e32 v57, v57
	v_add_f32_e32 v213, v41, v213
	v_exp_f32_e32 v58, v58
	v_add_f32_e32 v213, v42, v213
	v_exp_f32_e32 v59, v59
	v_add_f32_e32 v213, v43, v213
	v_exp_f32_e32 v60, v60
	v_add_f32_e32 v213, v44, v213
	v_exp_f32_e32 v61, v61
	v_add_f32_e32 v213, v45, v213
	v_exp_f32_e32 v62, v62
	v_add_f32_e32 v213, v46, v213
	v_exp_f32_e32 v63, v63
	v_add_f32_e32 v213, v47, v213
	s_nop 0
	v_add_f32_e32 v237, v48, v49
	v_add_f32_e32 v237, v50, v237
	v_add_f32_e32 v237, v51, v237
	v_add_f32_e32 v237, v52, v237
	v_add_f32_e32 v237, v53, v237
	v_add_f32_e32 v237, v54, v237
	v_add_f32_e32 v237, v55, v237
	v_add_f32_e32 v237, v56, v237
	v_add_f32_e32 v237, v57, v237
	v_add_f32_e32 v237, v58, v237
	v_add_f32_e32 v237, v59, v237
	v_add_f32_e32 v237, v60, v237
	v_add_f32_e32 v237, v61, v237
	v_add_f32_e32 v237, v62, v237
	v_add_f32_e32 v237, v63, v237
	v_add_f32_e32 v213, v237, v213
	v_cvt_pk_bf16_f32 v32, v32, v33
	v_cvt_pk_bf16_f32 v33, v34, v35
	v_cvt_pk_bf16_f32 v34, v36, v37
	v_cvt_pk_bf16_f32 v35, v38, v39
	v_cvt_pk_bf16_f32 v36, v40, v41
	v_cvt_pk_bf16_f32 v37, v42, v43
	v_cvt_pk_bf16_f32 v38, v44, v45
	v_cvt_pk_bf16_f32 v39, v46, v47
	v_cvt_pk_bf16_f32 v48, v48, v49
	v_cvt_pk_bf16_f32 v49, v50, v51
	v_cvt_pk_bf16_f32 v50, v52, v53
	v_cvt_pk_bf16_f32 v51, v54, v55
	v_cvt_pk_bf16_f32 v52, v56, v57
	v_cvt_pk_bf16_f32 v53, v58, v59
	v_cvt_pk_bf16_f32 v54, v60, v61
	v_cvt_pk_bf16_f32 v55, v62, v63
	s_waitcnt lgkmcnt(0)
	s_nop 1
	v_mfma_f32_32x32x16_bf16 v[0:15], v[32:35], v[64:67], v[0:15]
	v_mfma_f32_32x32x16_bf16 v[16:31], v[32:35], v[80:83], v[16:31]
	v_mfma_f32_32x32x16_bf16 v[0:15], v[36:39], v[68:71], v[0:15]
	v_mfma_f32_32x32x16_bf16 v[16:31], v[36:39], v[84:87], v[16:31]
	v_mfma_f32_32x32x16_bf16 v[0:15], v[48:51], v[72:75], v[0:15]
	v_mfma_f32_32x32x16_bf16 v[16:31], v[48:51], v[88:91], v[16:31]
	v_mfma_f32_32x32x16_bf16 v[0:15], v[52:55], v[76:79], v[0:15]
	v_mfma_f32_32x32x16_bf16 v[16:31], v[52:55], v[92:95], v[16:31]
	v_mov_b32_e32 v237, v213
	s_nop 1
	v_permlane32_swap_b32_e32 v213, v237
	v_add_f32_e32 v213, v213, v237
	s_and_saveexec_b64 s[4:5], s[2:3]
	s_cbranch_execz .LBB0_552
	ds_write_b32 v211, v213
	s_branch .LBB0_552
.Lrare_a:
	v_mov_b32_e32 v155, v215
	s_nop 1
	v_permlane32_swap_b32_e32 v215, v155
	v_max_f32_e32 v215, v215, v155
	v_max_f32_e32 v152, 0, v215
	v_sub_f32_e32 v238, v238, v152
	v_mov_b32_e32 v239, v238
	v_mov_b32_e32 v240, v238
	v_mov_b32_e32 v241, v238
	v_mov_b32_e32 v242, v238
	v_mov_b32_e32 v243, v238
	v_mov_b32_e32 v244, v238
	v_mov_b32_e32 v245, v238
	v_mov_b32_e32 v246, v238
	v_mov_b32_e32 v247, v238
	v_mov_b32_e32 v248, v238
	v_mov_b32_e32 v249, v238
	v_mov_b32_e32 v250, v238
	v_mov_b32_e32 v251, v238
	v_mov_b32_e32 v252, v238
	v_mov_b32_e32 v253, v238
	v_sub_f32_e32 v153, 0, v152
	v_exp_f32_e32 v153, v153
	v_sub_f32_e32 v48, v48, v152
	v_sub_f32_e32 v49, v49, v152
	v_sub_f32_e32 v50, v50, v152
	v_sub_f32_e32 v51, v51, v152
	v_sub_f32_e32 v52, v52, v152
	v_sub_f32_e32 v53, v53, v152
	v_sub_f32_e32 v54, v54, v152
	v_sub_f32_e32 v55, v55, v152
	v_sub_f32_e32 v56, v56, v152
	v_sub_f32_e32 v57, v57, v152
	v_sub_f32_e32 v58, v58, v152
	v_sub_f32_e32 v59, v59, v152
	v_sub_f32_e32 v60, v60, v152
	v_sub_f32_e32 v61, v61, v152
	v_sub_f32_e32 v62, v62, v152
	v_sub_f32_e32 v63, v63, v152
	v_mul_f32_e32 v213, v213, v153
	v_sub_f32_e32 v154, v80, v152
	v_sub_f32_e32 v156, v81, v152
	v_exp_f32_e32 v32, v154
	v_sub_f32_e32 v154, v82, v152
	v_exp_f32_e32 v33, v156
	v_sub_f32_e32 v156, v83, v152
	v_exp_f32_e32 v34, v154
	v_sub_f32_e32 v154, v84, v152
	v_exp_f32_e32 v35, v156
	v_sub_f32_e32 v156, v85, v152
	v_exp_f32_e32 v36, v154
	v_sub_f32_e32 v154, v86, v152
	v_exp_f32_e32 v37, v156
	v_sub_f32_e32 v156, v87, v152
	v_exp_f32_e32 v38, v154
	v_sub_f32_e32 v154, v88, v152
	v_exp_f32_e32 v39, v156
	v_sub_f32_e32 v156, v89, v152
	v_exp_f32_e32 v40, v154
	v_sub_f32_e32 v154, v90, v152
	v_exp_f32_e32 v41, v156
	v_sub_f32_e32 v156, v91, v152
	v_exp_f32_e32 v42, v154
	v_sub_f32_e32 v154, v92, v152
	v_exp_f32_e32 v43, v156
	v_sub_f32_e32 v156, v93, v152
	v_exp_f32_e32 v44, v154
	v_sub_f32_e32 v154, v94, v152
	v_exp_f32_e32 v45, v156
	v_sub_f32_e32 v156, v95, v152
	v_exp_f32_e32 v46, v154
	v_exp_f32_e32 v47, v156
	s_nop 0
	s_and_saveexec_b64 s[58:59], s[2:3]
	ds_write_b32 v211, v153 offset:128
	s_or_b64 exec, exec, s[58:59]
	s_waitcnt lgkmcnt(0)
	v_add_u32_e32 v237, s62, v232
	ds_read_b128 v[80:83], v237 offset:224
	ds_read_b128 v[84:87], v237 offset:192
	ds_read_b128 v[88:91], v237 offset:160
	ds_read_b128 v[92:95], v237 offset:128
	s_waitcnt lgkmcnt(0)
	v_pk_mul_f32 v[12:13], v[12:13], v[80:81]
	v_pk_mul_f32 v[8:9], v[8:9], v[84:85]
	v_pk_mul_f32 v[4:5], v[4:5], v[88:89]
	v_pk_mul_f32 v[14:15], v[14:15], v[82:83]
	v_pk_mul_f32 v[10:11], v[10:11], v[86:87]
	v_pk_mul_f32 v[6:7], v[6:7], v[90:91]
	v_pk_mul_f32 v[2:3], v[2:3], v[94:95]
	v_pk_mul_f32 v[0:1], v[0:1], v[92:93]
	v_pk_mul_f32 v[28:29], v[28:29], v[80:81]
	v_pk_mul_f32 v[24:25], v[24:25], v[84:85]
	v_pk_mul_f32 v[20:21], v[20:21], v[88:89]
	v_pk_mul_f32 v[30:31], v[30:31], v[82:83]
	v_pk_mul_f32 v[26:27], v[26:27], v[86:87]
	v_pk_mul_f32 v[22:23], v[22:23], v[90:91]
	v_pk_mul_f32 v[18:19], v[18:19], v[94:95]
	v_pk_mul_f32 v[16:17], v[16:17], v[92:93]
	s_branch .Ljoin_a
; #define FMA_S(x) asm("v_fma_f32 %0, %1, %2, %3" : "=v"(x) : "v"(x), "v"(Cv), "v"(mnC))
; __device__ __forceinline__ void partialSM(f32x16& p0, f32x16& p1, float& m_reg, float& mn, float& alpha) {
;   constexpr float C = SCALE * 1.4426950408889634f;
;   float pmax = p0[0];
; #pragma unroll
;   for (int r = 1; r < 16; ++r) pmax = fmaxf(pmax, p0[r]);
; #pragma unroll
;   for (int r = 0; r < 16; ++r) pmax = fmaxf(pmax, p1[r]);
;   { auto rr = __builtin_amdgcn_permlane32_swap(__float_as_uint(pmax), __float_as_uint(pmax), false, false);
;     pmax = fmaxf(__uint_as_float(rr[0]), __uint_as_float(rr[1])); }
;   if (__builtin_expect(__all(pmax - m_reg <= THR / SCALE), 1)) { mn = m_reg; alpha = 1.f; }
;   else { mn = fmaxf(m_reg, pmax); alpha = __builtin_amdgcn_exp2f((m_reg - mn) * C); m_reg = mn; }
;   const float mnC = -mn * C;
;     ...
;   float Cv = C; asm volatile("" : "+v"(Cv));
; #pragma unroll
;   for (int r = 0; r < 16; ++r) FMA_S(p0[r]);
; #pragma unroll
;   for (int r = 0; r < 16; ++r) FMA_S(p1[r]);
;     ...
; #pragma unroll
;   for (int r = 0; r < 16; ++r) p0[r] = __builtin_amdgcn_exp2f(p0[r]);
; }
.Lrare_b:
	v_mov_b32_e32 v155, v215
	s_nop 1
	v_permlane32_swap_b32_e32 v215, v155
	v_max_f32_e32 v215, v215, v155
	v_max_f32_e32 v152, 0, v215
	v_sub_f32_e32 v238, v238, v152
	v_mov_b32_e32 v239, v238
	v_mov_b32_e32 v240, v238
	v_mov_b32_e32 v241, v238
	v_mov_b32_e32 v242, v238
	v_mov_b32_e32 v243, v238
	v_mov_b32_e32 v244, v238
	v_mov_b32_e32 v245, v238
	v_mov_b32_e32 v246, v238
	v_mov_b32_e32 v247, v238
	v_mov_b32_e32 v248, v238
	v_mov_b32_e32 v249, v238
	v_mov_b32_e32 v250, v238
	v_mov_b32_e32 v251, v238
	v_mov_b32_e32 v252, v238
	v_mov_b32_e32 v253, v238
	v_sub_f32_e32 v153, 0, v152
	v_exp_f32_e32 v153, v153
	v_sub_f32_e32 v64, v64, v152
	v_sub_f32_e32 v65, v65, v152
	v_sub_f32_e32 v66, v66, v152
	v_sub_f32_e32 v67, v67, v152
	v_sub_f32_e32 v68, v68, v152
	v_sub_f32_e32 v69, v69, v152
	v_sub_f32_e32 v70, v70, v152
	v_sub_f32_e32 v71, v71, v152
	v_sub_f32_e32 v72, v72, v152
	v_sub_f32_e32 v73, v73, v152
	v_sub_f32_e32 v74, v74, v152
	v_sub_f32_e32 v75, v75, v152
	v_sub_f32_e32 v76, v76, v152
	v_sub_f32_e32 v77, v77, v152
	v_sub_f32_e32 v78, v78, v152
	v_sub_f32_e32 v79, v79, v152
	v_mul_f32_e32 v213, v213, v153
	v_sub_f32_e32 v154, v80, v152
	v_sub_f32_e32 v156, v81, v152
	v_exp_f32_e32 v32, v154
	v_sub_f32_e32 v154, v82, v152
	v_exp_f32_e32 v33, v156
	v_sub_f32_e32 v156, v83, v152
	v_exp_f32_e32 v34, v154
	v_sub_f32_e32 v154, v84, v152
	v_exp_f32_e32 v35, v156
	v_sub_f32_e32 v156, v85, v152
	v_exp_f32_e32 v36, v154
	v_sub_f32_e32 v154, v86, v152
	v_exp_f32_e32 v37, v156
	v_sub_f32_e32 v156, v87, v152
	v_exp_f32_e32 v38, v154
	v_sub_f32_e32 v154, v88, v152
	v_exp_f32_e32 v39, v156
	v_sub_f32_e32 v156, v89, v152
	v_exp_f32_e32 v40, v154
	v_sub_f32_e32 v154, v90, v152
	v_exp_f32_e32 v41, v156
	v_sub_f32_e32 v156, v91, v152
	v_exp_f32_e32 v42, v154
	v_sub_f32_e32 v154, v92, v152
	v_exp_f32_e32 v43, v156
	v_sub_f32_e32 v156, v93, v152
	v_exp_f32_e32 v44, v154
	v_sub_f32_e32 v154, v94, v152
	v_exp_f32_e32 v45, v156
	v_sub_f32_e32 v156, v95, v152
	v_exp_f32_e32 v46, v154
	v_exp_f32_e32 v47, v156
	s_nop 0
	s_and_saveexec_b64 s[60:61], s[2:3]
	ds_write_b32 v211, v153 offset:128
	s_or_b64 exec, exec, s[60:61]
	s_waitcnt lgkmcnt(0)
	v_add_u32_e32 v237, s62, v232
	ds_read_b128 v[80:83], v237 offset:224
	ds_read_b128 v[84:87], v237 offset:192
	ds_read_b128 v[88:91], v237 offset:160
	ds_read_b128 v[92:95], v237 offset:128
	s_waitcnt lgkmcnt(0)
	v_pk_mul_f32 v[12:13], v[12:13], v[80:81]
	v_pk_mul_f32 v[8:9], v[8:9], v[84:85]
	v_pk_mul_f32 v[4:5], v[4:5], v[88:89]
	v_pk_mul_f32 v[14:15], v[14:15], v[82:83]
	v_pk_mul_f32 v[10:11], v[10:11], v[86:87]
	v_pk_mul_f32 v[6:7], v[6:7], v[90:91]
	v_pk_mul_f32 v[2:3], v[2:3], v[94:95]
	v_pk_mul_f32 v[0:1], v[0:1], v[92:93]
	v_pk_mul_f32 v[28:29], v[28:29], v[80:81]
	v_pk_mul_f32 v[24:25], v[24:25], v[84:85]
	v_pk_mul_f32 v[20:21], v[20:21], v[88:89]
	v_pk_mul_f32 v[30:31], v[30:31], v[82:83]
	v_pk_mul_f32 v[26:27], v[26:27], v[86:87]
	v_pk_mul_f32 v[22:23], v[22:23], v[90:91]
	v_pk_mul_f32 v[18:19], v[18:19], v[94:95]
	v_pk_mul_f32 v[16:17], v[16:17], v[92:93]
	s_branch .Ljoin_b
.Lrare_t:
	v_mov_b32_e32 v155, v215
	s_nop 1
	v_permlane32_swap_b32_e32 v215, v155
	v_max_f32_e32 v215, v215, v155
	v_max_f32_e32 v152, 0, v215
	v_sub_f32_e32 v238, v238, v152
	v_mov_b32_e32 v239, v238
	v_mov_b32_e32 v240, v238
	v_mov_b32_e32 v241, v238
	v_mov_b32_e32 v242, v238
	v_mov_b32_e32 v243, v238
	v_mov_b32_e32 v244, v238
	v_mov_b32_e32 v245, v238
	v_mov_b32_e32 v246, v238
	v_mov_b32_e32 v247, v238
	v_mov_b32_e32 v248, v238
	v_mov_b32_e32 v249, v238
	v_mov_b32_e32 v250, v238
	v_mov_b32_e32 v251, v238
	v_mov_b32_e32 v252, v238
	v_mov_b32_e32 v253, v238
	v_sub_f32_e32 v153, 0, v152
	v_exp_f32_e32 v153, v153
	v_sub_f32_e32 v48, v48, v152
	v_sub_f32_e32 v49, v49, v152
	v_sub_f32_e32 v50, v50, v152
	v_sub_f32_e32 v51, v51, v152
	v_sub_f32_e32 v52, v52, v152
	v_sub_f32_e32 v53, v53, v152
	v_sub_f32_e32 v54, v54, v152
	v_sub_f32_e32 v55, v55, v152
	v_sub_f32_e32 v56, v56, v152
	v_sub_f32_e32 v57, v57, v152
	v_sub_f32_e32 v58, v58, v152
	v_sub_f32_e32 v59, v59, v152
	v_sub_f32_e32 v60, v60, v152
	v_sub_f32_e32 v61, v61, v152
	v_sub_f32_e32 v62, v62, v152
	v_sub_f32_e32 v63, v63, v152
	v_mul_f32_e32 v213, v213, v153
	v_sub_f32_e32 v154, v80, v152
	v_sub_f32_e32 v156, v81, v152
	v_exp_f32_e32 v32, v154
	v_sub_f32_e32 v154, v82, v152
	v_exp_f32_e32 v33, v156
	v_sub_f32_e32 v156, v83, v152
	v_exp_f32_e32 v34, v154
	v_sub_f32_e32 v154, v84, v152
	v_exp_f32_e32 v35, v156
	v_sub_f32_e32 v156, v85, v152
	v_exp_f32_e32 v36, v154
	v_sub_f32_e32 v154, v86, v152
	v_exp_f32_e32 v37, v156
	v_sub_f32_e32 v156, v87, v152
	v_exp_f32_e32 v38, v154
	v_sub_f32_e32 v154, v88, v152
	v_exp_f32_e32 v39, v156
	v_sub_f32_e32 v156, v89, v152
	v_exp_f32_e32 v40, v154
	v_sub_f32_e32 v154, v90, v152
	v_exp_f32_e32 v41, v156
	v_sub_f32_e32 v156, v91, v152
	v_exp_f32_e32 v42, v154
	v_sub_f32_e32 v154, v92, v152
	v_exp_f32_e32 v43, v156
	v_sub_f32_e32 v156, v93, v152
	v_exp_f32_e32 v44, v154
	v_sub_f32_e32 v154, v94, v152
	v_exp_f32_e32 v45, v156
	v_sub_f32_e32 v156, v95, v152
	v_exp_f32_e32 v46, v154
	v_exp_f32_e32 v47, v156
	s_nop 0
	s_and_saveexec_b64 s[56:57], s[2:3]
	ds_write_b32 v211, v153 offset:128
	s_or_b64 exec, exec, s[56:57]
	s_waitcnt lgkmcnt(0)
	v_add_u32_e32 v237, s62, v232
	ds_read_b128 v[80:83], v237 offset:224
	ds_read_b128 v[84:87], v237 offset:192
	ds_read_b128 v[88:91], v237 offset:160
	ds_read_b128 v[92:95], v237 offset:128
	s_waitcnt lgkmcnt(0)
	v_pk_mul_f32 v[12:13], v[12:13], v[80:81]
	v_pk_mul_f32 v[8:9], v[8:9], v[84:85]
	v_pk_mul_f32 v[4:5], v[4:5], v[88:89]
	v_pk_mul_f32 v[14:15], v[14:15], v[82:83]
	v_pk_mul_f32 v[10:11], v[10:11], v[86:87]
	v_pk_mul_f32 v[6:7], v[6:7], v[90:91]
	v_pk_mul_f32 v[2:3], v[2:3], v[94:95]
	v_pk_mul_f32 v[0:1], v[0:1], v[92:93]
	v_pk_mul_f32 v[28:29], v[28:29], v[80:81]
	v_pk_mul_f32 v[24:25], v[24:25], v[84:85]
	v_pk_mul_f32 v[20:21], v[20:21], v[88:89]
	v_pk_mul_f32 v[30:31], v[30:31], v[82:83]
	v_pk_mul_f32 v[26:27], v[26:27], v[86:87]
	v_pk_mul_f32 v[22:23], v[22:23], v[90:91]
	v_pk_mul_f32 v[18:19], v[18:19], v[94:95]
	v_pk_mul_f32 v[16:17], v[16:17], v[92:93]
	s_branch .Ljoin_t

; __device__ __forceinline__ void xcd_barrier(const XcdBarrier& b) {
;     asm volatile("s_waitcnt vmcnt(0)" ::: "memory");
;     __syncthreads();
;     if (threadIdx.x == 0) {
;         unsigned* bar = b.bar;
;         __builtin_amdgcn_s_waitcnt(0);
;         unsigned nloc = b.st[0], nx = b.st[1];
;         if (nloc == 0u) { xcd_barrier_complete(bar, b.x, nloc, nx); b.st[0] = nloc; b.st[1] = nx; }
.LBB0_606:
	s_nop 0
	s_nop 0
	s_cmp_gt_i32 s31, 4
	s_cselect_b64 s[2:3], -1, 0
	s_and_b64 s[0:1], s[0:1], s[2:3]
	s_andn2_b64 vcc, exec, s[0:1]
	s_cbranch_vccnz .LBB0_660
	s_waitcnt vmcnt(0)
	s_waitcnt vmcnt(0) lgkmcnt(0)
	s_barrier
	s_and_saveexec_b64 s[0:1], s[82:83]
	s_cbranch_execz .LBB0_659
	s_add_i32 s4, 0, 0x22000
	v_mov_b32_e32 v0, s4
	s_waitcnt vmcnt(0) expcnt(0) lgkmcnt(0)
	ds_read_b32 v2, v0
	s_add_i32 s4, 0, 0x22004
	v_mov_b32_e32 v0, s4
	ds_read_b32 v0, v0
	s_waitcnt lgkmcnt(1)
	v_cmp_ne_u32_e32 vcc, 0, v2
	s_cbranch_vccnz .LBB0_623
	v_readlane_b32 s4, v254, 0
	s_mul_i32 s18, s93, s4
	s_add_u32 s4, s28, 0x1000
	s_addc_u32 s5, s29, 0
	s_add_u32 s6, s28, 0x1100
	s_addc_u32 s7, s29, 0
	s_add_u32 s8, s28, 0x1200
	s_addc_u32 s9, s29, 0
	s_add_u32 s10, s28, 0x1300
	s_mul_i32 s18, s18, s92
	s_addc_u32 s11, s29, 0
	s_mov_b32 s19, 1
	v_mov_b32_e32 v16, 0
	s_branch .LBB0_611
